# baseline (speedup 1.0000x reference)
.LBB0_987:
	s_or_b64 exec, exec, s[12:13]
	s_waitcnt vmcnt(0)
	s_branch .LBB0_988
.Lburn6:
	s_or_b64 exec, exec, s[0:1]
	v_mov_b32_e32 v230, 0x22008
	s_mov_b32 s3, 0
.Lburn6_loop:
	v_mfma_f32_16x16x32_bf16 v[222:225], v[226:229], v[226:229], v[222:225]
	v_mfma_f32_16x16x32_bf16 v[232:235], v[226:229], v[226:229], v[232:235]
	v_mfma_f32_16x16x32_bf16 v[236:239], v[226:229], v[226:229], v[236:239]
	v_mfma_f32_16x16x32_bf16 v[240:243], v[226:229], v[226:229], v[240:243]
	v_mfma_f32_16x16x32_bf16 v[222:225], v[226:229], v[226:229], v[222:225]
	v_mfma_f32_16x16x32_bf16 v[232:235], v[226:229], v[226:229], v[232:235]
	v_mfma_f32_16x16x32_bf16 v[236:239], v[226:229], v[226:229], v[236:239]
	v_mfma_f32_16x16x32_bf16 v[240:243], v[226:229], v[226:229], v[240:243]
	v_mfma_f32_16x16x32_bf16 v[222:225], v[226:229], v[226:229], v[222:225]
	v_mfma_f32_16x16x32_bf16 v[232:235], v[226:229], v[226:229], v[232:235]
	v_mfma_f32_16x16x32_bf16 v[236:239], v[226:229], v[226:229], v[236:239]
	v_mfma_f32_16x16x32_bf16 v[240:243], v[226:229], v[226:229], v[240:243]
	v_mfma_f32_16x16x32_bf16 v[222:225], v[226:229], v[226:229], v[222:225]
	v_mfma_f32_16x16x32_bf16 v[232:235], v[226:229], v[226:229], v[232:235]
	v_mfma_f32_16x16x32_bf16 v[236:239], v[226:229], v[226:229], v[236:239]
	v_mfma_f32_16x16x32_bf16 v[240:243], v[226:229], v[226:229], v[240:243]
	ds_read_b32 v231, v230
	s_waitcnt lgkmcnt(0)
	v_readfirstlane_b32 s2, v231
	s_nop 3
	s_add_u32 s3, s3, 1
	s_cmp_ge_u32 s2, 6
	s_cbranch_scc1 .LBB0_988
	s_cmp_lt_u32 s3, 0x20000
	s_cbranch_scc1 .Lburn6_loop
.LBB0_988:
	s_or_b64 exec, exec, s[0:1]
	v_mov_b32_e32 v0, 6
	v_mov_b32_e32 v1, 0x22008
	ds_write_b32 v1, v0
	s_add_u32 s10, s60, 0x10000000
	s_addc_u32 s11, s61, 0
	v_mov_b32_e32 v144, v218
	s_waitcnt lgkmcnt(0)
	s_barrier
	s_cmpk_gt_i32 s70, 0x7ff
	v_readfirstlane_b32 s15, v144
	s_cbranch_scc1 .LBB0_1012
	s_ashr_i32 s0, s70, 31
	s_lshr_b32 s0, s0, 29
	s_add_i32 s3, s70, s0
	s_and_b32 s0, s3, -8
	s_sub_i32 s2, s70, s0
	s_cmp_gt_i32 s2, -1
	s_cbranch_scc0 .LBB0_991
	s_lshl_b32 s4, s2, 8
	s_cbranch_execz .LBB0_992
	s_branch .LBB0_993
